# stagger GEMM phase start per CU within an XCD ((block>>3)*0.65us) for multi-unit GEMM phases
# baseline (speedup 1.0000x reference)
;     __host__ __device__ bool next(int i, Unit& u) const {
;         const long L = (long)i * G + c; if (L >= nwg) return false;
;         int wgid = (int)L; { const int q = nwg / NXCD, r = nwg % NXCD, xcd = wgid % NXCD, off = wgid / NXCD; wgid = (xcd < r ? xcd * (q + 1) : r * (q + 1) + (xcd - r) * q) + off; }
; template <class Epi, class Sched, bool ALIGN_EPI = false, bool SP2 = false>
; __device__ __forceinline__ void gemm_phase(PG8_LAS unsigned char* lds, const Gemm g, const Sched& S, const Epi& E) {
;     ...
;     if (!S.next(0, cur)) return;
.LBB0_39:
	s_andn2_b64 vcc, exec, s[14:15]
	v_writelane_b32 v253, s27, 27
	s_cbranch_vccnz .LBB0_80
	s_lshl_b32 s90, s20, 5
	s_cmp_lt_i32 s68, s90
	v_readfirstlane_b32 s23, v210
	s_cbranch_scc0 .LBB0_80
	s_cmp_lt_u32 s20, 9
	s_cbranch_scc1 .Lstg_skip
	s_and_b32 s28, s68, 7
	s_mul_i32 s28, s28, 0
	s_lshr_b32 s29, s68, 3
	s_mul_i32 s29, s29, 65
	s_add_u32 s28, s28, s29
	s_memrealtime s[24:25]
	s_waitcnt lgkmcnt(0)
